# P5 table builder: 12 conv-weight loads in one batch instead of 6 serialized round trips; P7 modulation reduce: both tasks in one pass; on v48 stack
# speedup vs baseline: 1.0076x; 1.0076x over previous
; #define LAS __attribute__((address_space(3)))
; __device__ __forceinline__ void gp_tables(Frame& F, int cidx, LAS float* Gs, int lane) {
;     ...
;     const int h = (cidx >> 6) & 15; LAS float* cwl = (LAS float*)(F.lds + GP_CW);
; #pragma unroll
;     for (int r = 0; r < 12; ++r) { const int type = r >> 2, tap = r & 3;
;         const float* src = F.gdn_conv_w + (size_t)tap * 6144 + type * GDNW + h * HD + 2 * lane;
;         cwl[r * 128 + 2 * lane] = src[0]; cwl[r * 128 + 2 * lane + 1] = src[1]; }
.LBB0_1059:
	s_or_b64 exec, exec, s[22:23]
	s_lshl_b32 s11, s18, 9
	v_readlane_b32 s36, v252, 18
	s_and_b32 s11, s11, 0x1e00
	v_readlane_b32 s38, v252, 20
	v_lshlrev_b32_e32 v114, 3, v127
	v_readlane_b32 s39, v252, 21
	s_add_u32 s18, s38, s11
	v_add_u32_e32 v116, 0, v114
	s_addc_u32 s19, s39, 0
	v_add_u32_e32 v131, 0x20800, v116
	global_load_dwordx2 v[166:167], v114, s[18:19]
	v_readlane_b32 s18, v251, 46
	s_add_u32 s18, s18, s11
	v_readlane_b32 s19, v251, 47
	s_addc_u32 s19, s19, 0
	s_movk_i32 s27, 0x110
	v_readlane_b32 s37, v252, 19
	v_readlane_b32 s40, v252, 22
	v_readlane_b32 s41, v252, 23
	global_load_dwordx2 v[168:169], v114, s[18:19]
	v_readlane_b32 s18, v251, 48
	s_add_u32 s18, s18, s11
	v_readlane_b32 s19, v251, 49
	s_addc_u32 s19, s19, 0
	v_readlane_b32 s42, v252, 24
	v_readlane_b32 s43, v252, 25
	v_readlane_b32 s44, v252, 26
	v_readlane_b32 s45, v252, 27
	v_readlane_b32 s46, v252, 28
	v_readlane_b32 s47, v252, 29
	v_readlane_b32 s48, v252, 30
	v_readlane_b32 s49, v252, 31
	v_readlane_b32 s50, v252, 32
	v_readlane_b32 s51, v252, 33
	global_load_dwordx2 v[170:171], v114, s[18:19]
	v_readlane_b32 s18, v251, 50
	s_add_u32 s18, s18, s11
	v_readlane_b32 s19, v251, 51
	s_addc_u32 s19, s19, 0
	s_nop 3
	global_load_dwordx2 v[172:173], v114, s[18:19]
	v_readlane_b32 s18, v251, 52
	s_add_u32 s18, s18, s11
	v_readlane_b32 s19, v251, 53
	s_addc_u32 s19, s19, 0
	s_nop 1
	global_load_dwordx2 v[174:175], v114, s[18:19]
	v_readlane_b32 s18, v251, 54
	s_add_u32 s18, s18, s11
	v_readlane_b32 s19, v251, 55
	s_addc_u32 s19, s19, 0
	s_nop 3
	global_load_dwordx2 v[176:177], v114, s[18:19]
	v_readlane_b32 s18, v251, 56
	s_add_u32 s18, s18, s11
	v_readlane_b32 s19, v251, 57
	s_addc_u32 s19, s19, 0
	s_nop 1
	global_load_dwordx2 v[178:179], v114, s[18:19]
	v_readlane_b32 s18, v251, 58
	s_add_u32 s18, s18, s11
	v_readlane_b32 s19, v251, 59
	s_addc_u32 s19, s19, 0
	s_nop 3
	global_load_dwordx2 v[180:181], v114, s[18:19]
	v_readlane_b32 s18, v251, 60
	s_add_u32 s18, s18, s11
	v_readlane_b32 s19, v251, 61
	s_addc_u32 s19, s19, 0
	s_nop 1
	global_load_dwordx2 v[182:183], v114, s[18:19]
	v_readlane_b32 s18, v251, 62
	s_add_u32 s18, s18, s11
	v_readlane_b32 s19, v251, 63
	s_addc_u32 s19, s19, 0
	s_nop 3
	global_load_dwordx2 v[184:185], v114, s[18:19]
	v_readlane_b32 s18, v250, 0
	s_add_u32 s18, s18, s11
	v_readlane_b32 s19, v250, 1
	s_addc_u32 s19, s19, 0
	s_nop 1
	global_load_dwordx2 v[186:187], v114, s[18:19]
	v_readlane_b32 s18, v250, 2
	s_add_u32 s18, s18, s11
	v_readlane_b32 s11, v250, 3
	s_addc_u32 s19, s11, 0
	s_nop 1
	global_load_dwordx2 v[188:189], v114, s[18:19]
	s_waitcnt vmcnt(0)
	ds_write2st64_b64 v131, v[166:167], v[168:169] offset1:1
	ds_write2st64_b64 v131, v[170:171], v[172:173] offset0:2 offset1:3
	ds_write2st64_b64 v131, v[174:175], v[176:177] offset0:4 offset1:5
	ds_write2st64_b64 v131, v[178:179], v[180:181] offset0:6 offset1:7
	ds_write2st64_b64 v131, v[182:183], v[184:185] offset0:8 offset1:9
	ds_write2st64_b64 v131, v[186:187], v[188:189] offset0:10 offset1:11

; #define LAS __attribute__((address_space(3)))
; __device__ __forceinline__ void p1_modreduce(Frame& F, int n_lo, int n_hi) {
;     const float* modp = (const float*)(F.ws + WS_MODP); float* mod = (float*)(F.ws + WS_MOD);
;     const int nn = n_hi - n_lo, ntask = 2 * nn / 64;
;     LAS float* red = (LAS float*)(F.lds + RING_OFF);
;     for (int task = F.vcu; task < ntask; task += F.G) {
;         const int b = task / (nn / 64), n = n_lo + (task % (nn / 64)) * 64 + F.lane;
;         const float* p = modp + (size_t)(F.wave * 8 * 2 + b) * NMOD + n;
;         float v[8];
; #pragma unroll
;         for (int k = 0; k < 8; ++k) v[k] = p[(size_t)k * 2 * NMOD];
;         red[F.wave * 64 + F.lane] = ((v[0] + v[1]) + (v[2] + v[3])) + ((v[4] + v[5]) + (v[6] + v[7]));
;         __syncthreads();
;         if (F.wave == 0) { float s = F.b_ada[n];
; #pragma unroll
;             for (int w = 0; w < NWAVES; ++w) s += red[w * 64 + F.lane];
;             mod[(size_t)b * NMOD + n] = s; }
;         __syncthreads();
;     }
; }
.LBB0_1681:
	s_cmp_lt_i32 s86, 8
	s_cselect_b64 s[0:1], -1, 0
	s_cmp_gt_i32 s87, 7
	s_cselect_b64 s[4:5], -1, 0
	s_and_b64 s[0:1], s[0:1], s[4:5]
	s_andn2_b64 vcc, exec, s[0:1]
	s_cbranch_vccnz .LBB0_1741
	v_mov_b32_e32 v1, v0
	s_nop 0
	v_readfirstlane_b32 s0, v1
	s_ashr_i32 s2, s0, 6
	s_cmpk_lt_i32 s3, 0x78
	v_and_b32_e32 v4, 63, v1
	s_cbranch_scc1 .LBB0_1688
	s_cmpk_gt_i32 s88, 0x1ff
	s_cbranch_scc1 .LBB0_1688
	s_add_u32 s4, s82, 0x800000
	s_addc_u32 s5, s83, 0
	s_add_u32 s6, s82, 0x100000
	s_addc_u32 s7, s83, 0
	s_lshl_b32 s1, s2, 8
	s_lshl_b32 s8, s2, 4
	s_add_i32 s1, s1, 0
	v_lshlrev_b32_e32 v2, 2, v4
	s_cmp_lt_u32 s0, 64
	v_add_u32_e32 v1, s1, v2
	s_cselect_b64 s[0:1], -1, 0
	v_add_u32_e32 v5, 0, v2
	v_lshl_or_b32 v2, s88, 6, v4
	s_waitcnt vmcnt(0)
	v_add_u32_e32 v6, 0x2000, v2
	v_cndmask_b32_e64 v2, 0, 1, s[0:1]
	s_lshl_b32 s9, s3, 6
	s_mov_b32 s10, 0x30000
	s_mov_b32 s11, 0x60000
	s_mov_b32 s12, 0x90000
	s_mov_b32 s13, 0xc0000
	s_mov_b32 s14, 0xf0000
	s_mov_b32 s15, 0x120000
	s_mov_b32 s16, 0x150000
	v_cmp_ne_u32_e64 s[0:1], 1, v2
	s_mov_b32 s17, s88
	s_cmpk_lg_i32 s3, 0x100
	s_cbranch_scc1 .LBB0_1686
	v_readlane_b32 s42, v252, 8
	v_readlane_b32 s43, v252, 9
	v_lshlrev_b32_e32 v34, 2, v6
	s_mul_i32 s19, s8, 0x18000
	s_add_u32 s20, s4, s19
	s_addc_u32 s21, s5, 0
	global_load_dword v8, v34, s[20:21]
	s_add_u32 s10, s20, 0x30000
	s_addc_u32 s11, s21, 0
	global_load_dword v10, v34, s[10:11]
	s_add_u32 s10, s20, 0x60000
	s_addc_u32 s11, s21, 0
	global_load_dword v12, v34, s[10:11]
	s_add_u32 s10, s20, 0x90000
	s_addc_u32 s11, s21, 0
	global_load_dword v14, v34, s[10:11]
	s_add_u32 s10, s20, 0xc0000
	s_addc_u32 s11, s21, 0
	global_load_dword v9, v34, s[10:11]
	s_add_u32 s10, s20, 0xf0000
	s_addc_u32 s11, s21, 0
	global_load_dword v11, v34, s[10:11]
	s_add_u32 s10, s20, 0x120000
	s_addc_u32 s11, s21, 0
	global_load_dword v13, v34, s[10:11]
	s_add_u32 s10, s20, 0x150000
	s_addc_u32 s11, s21, 0
	global_load_dword v15, v34, s[10:11]
	s_add_u32 s10, s20, 0x18000
	s_addc_u32 s11, s21, 0
	global_load_dword v24, v34, s[10:11]
	s_add_u32 s10, s20, 0x48000
	s_addc_u32 s11, s21, 0
	global_load_dword v26, v34, s[10:11]
	s_add_u32 s10, s20, 0x78000
	s_addc_u32 s11, s21, 0
	global_load_dword v28, v34, s[10:11]
	s_add_u32 s10, s20, 0xa8000
	s_addc_u32 s11, s21, 0
	global_load_dword v30, v34, s[10:11]
	s_add_u32 s10, s20, 0xd8000
	s_addc_u32 s11, s21, 0
	global_load_dword v25, v34, s[10:11]
	s_add_u32 s10, s20, 0x108000
	s_addc_u32 s11, s21, 0
	global_load_dword v27, v34, s[10:11]
	s_add_u32 s10, s20, 0x138000
	s_addc_u32 s11, s21, 0
	global_load_dword v29, v34, s[10:11]
	s_add_u32 s10, s20, 0x168000
	s_addc_u32 s11, s21, 0
	global_load_dword v31, v34, s[10:11]
	global_load_dword v32, v34, s[42:43]
	s_waitcnt vmcnt(0)
	v_pk_add_f32 v[8:9], v[8:9], v[10:11]
	v_pk_add_f32 v[10:11], v[12:13], v[14:15]
	v_pk_add_f32 v[24:25], v[24:25], v[26:27]
	v_pk_add_f32 v[26:27], v[28:29], v[30:31]
	s_nop 0
	v_pk_add_f32 v[8:9], v[8:9], v[10:11]
	v_pk_add_f32 v[24:25], v[24:25], v[26:27]
	s_nop 0
	v_add_f32_e32 v7, v8, v9
	v_add_f32_e32 v33, v24, v25
	ds_write_b32 v1, v7
	ds_write_b32 v1, v33 offset:2048
	s_waitcnt lgkmcnt(0)
	s_barrier
	s_cmp_gt_u32 s2, 1
	s_cbranch_scc1 .LBB0_1688
	s_lshl_b32 s10, s2, 11
	v_add_u32_e32 v35, s10, v5
	ds_read2st64_b32 v[8:9], v35 offset1:1
	ds_read2st64_b32 v[10:11], v35 offset0:2 offset1:3
	ds_read2st64_b32 v[12:13], v35 offset0:4 offset1:5
	ds_read2st64_b32 v[14:15], v35 offset0:6 offset1:7
	s_mul_i32 s10, s2, 0x18000
	s_add_u32 s18, s6, s10
	s_addc_u32 s19, s7, 0
	s_waitcnt lgkmcnt(0)
	v_add_f32_e32 v7, v32, v8
	v_add_f32_e32 v7, v7, v9
	v_add_f32_e32 v7, v7, v10
	v_add_f32_e32 v7, v7, v11
	v_add_f32_e32 v7, v7, v12
	v_add_f32_e32 v7, v7, v13
	v_add_f32_e32 v7, v7, v14
	v_add_f32_e32 v7, v7, v15
	global_store_dword v34, v7, s[18:19]
	s_branch .LBB0_1688
	s_branch .LBB0_1686
